# v48 + hgrn_r1 per-run final block (.LBB0_267): 24 serial ds_read_b128 through one quad replaced by double-buffered 3-quad read sets (v50-53, v214-233), counted lgkmcnt(3)/(0), s_nop 1 before the MFMA
# baseline (speedup 1.0000x reference)
; #define LAS __attribute__((address_space(3)))
; #define GAS __attribute__((address_space(1)))
; #define MFMA16(a, b, c) __builtin_amdgcn_mfma_f32_16x16x32_bf16((a), (b), (c), 0, 0, 0)
; __device__ __forceinline__ void hgrn_r1(const GAS bf16* proj, GAS float* RU, GAS float* RD, int TOKG, unsigned char* lds, int tid, int lane, int wave, int bid, int G) {
;     ...
;             { const LAS unsigned char* Lv = L + VS0 + (ci % 3) * VSET; const LAS unsigned char* Lk = L + (ci & 1) * KSET; const LAS float* decl = (const LAS float*)(Lk + 128 * HS);
;               bf16x8 vf[2];
; #pragma unroll
;               for (int ks = 0; ks < 2; ++ks) vf[ks] = *(const LAS bf16x8*)(Lv + (16 * wave + fr) * HS + (32 * ks + 8 * fq) * 2);
; #pragma unroll
;               for (int nk = 0; nk < 8; ++nk) { const f32x4h dk = *(const LAS f32x4h*)(decl + 16 * nk + 4 * fq); acc[nk] = acc[nk] * dk;
; #pragma unroll
;                   for (int ks = 0; ks < 2; ++ks) { const bf16x8 kf = *(const LAS bf16x8*)(Lk + (16 * nk + fr) * HS + (32 * ks + 8 * fq) * 2); acc[nk] = MFMA16(kf, vf[ks], acc[nk]); } } }
;             if (nxt) R1_B(ci + 1);
;         }
;         GAS float* sp = RU + (size_t)run * 16384 + (16 * wave + fr) * 128 + 4 * fq;
; #pragma unroll
;         for (int nk = 0; nk < 8; ++nk) *(GAS f32x4h*)(sp + 16 * nk) = acc[nk];
;         if (wave == 0) *(GAS f32x2h*)(RD + (size_t)run * 128 + 2 * lane) = (f32x2h){__builtin_amdgcn_exp2f(sum0), __builtin_amdgcn_exp2f(sum1)};
.LBB0_267:
	s_waitcnt lgkmcnt(0)
	s_barrier
	ds_read_b128 v[36:39], v42 offset:37888
	ds_read_b128 v[32:35], v42 offset:37952
	ds_read_b128 v[50:53], v40 offset:37376
	s_ashr_i32 s27, s26, 31
	s_lshl_b64 s[20:21], s[26:27], 16
	s_and_b64 vcc, exec, s[0:1]
	ds_read_b128 v[214:217], v90 offset:18944
	ds_read_b128 v[218:221], v90 offset:19008
	ds_read_b128 v[222:225], v40 offset:37440
	ds_read_b128 v[226:229], v90 offset:21248
	ds_read_b128 v[230:233], v90 offset:21312
	s_waitcnt lgkmcnt(3)
	v_pk_mul_f32 v[30:31], v[30:31], v[52:53]
	v_pk_mul_f32 v[28:29], v[28:29], v[50:51]
	s_nop 1
	v_mfma_f32_16x16x32_bf16 v[28:31], v[214:217], v[36:39], v[28:31]
	v_mfma_f32_16x16x32_bf16 v[28:31], v[218:221], v[32:35], v[28:31]
	ds_read_b128 v[50:53], v40 offset:37504
	ds_read_b128 v[214:217], v90 offset:23552
	ds_read_b128 v[218:221], v90 offset:23616
	s_waitcnt lgkmcnt(3)
	v_pk_mul_f32 v[26:27], v[26:27], v[224:225]
	v_pk_mul_f32 v[24:25], v[24:25], v[222:223]
	s_nop 1
	v_mfma_f32_16x16x32_bf16 v[24:27], v[226:229], v[36:39], v[24:27]
	v_mfma_f32_16x16x32_bf16 v[24:27], v[230:233], v[32:35], v[24:27]
	ds_read_b128 v[222:225], v40 offset:37568
	ds_read_b128 v[226:229], v90 offset:25856
	ds_read_b128 v[230:233], v90 offset:25920
	s_waitcnt lgkmcnt(3)
	v_pk_mul_f32 v[22:23], v[22:23], v[52:53]
	v_pk_mul_f32 v[20:21], v[20:21], v[50:51]
	s_nop 1
	v_mfma_f32_16x16x32_bf16 v[20:23], v[214:217], v[36:39], v[20:23]
	v_mfma_f32_16x16x32_bf16 v[20:23], v[218:221], v[32:35], v[20:23]
	ds_read_b128 v[50:53], v40 offset:37632
	ds_read_b128 v[214:217], v90 offset:28160
	ds_read_b128 v[218:221], v90 offset:28224
	s_waitcnt lgkmcnt(3)
	v_pk_mul_f32 v[18:19], v[18:19], v[224:225]
	v_pk_mul_f32 v[16:17], v[16:17], v[222:223]
	s_nop 1
	v_mfma_f32_16x16x32_bf16 v[16:19], v[226:229], v[36:39], v[16:19]
	v_mfma_f32_16x16x32_bf16 v[16:19], v[230:233], v[32:35], v[16:19]
	ds_read_b128 v[222:225], v40 offset:37696
	ds_read_b128 v[226:229], v90 offset:30464
	ds_read_b128 v[230:233], v90 offset:30528
	s_waitcnt lgkmcnt(3)
	v_pk_mul_f32 v[14:15], v[14:15], v[52:53]
	v_pk_mul_f32 v[12:13], v[12:13], v[50:51]
	s_nop 1
	v_mfma_f32_16x16x32_bf16 v[12:15], v[214:217], v[36:39], v[12:15]
	v_mfma_f32_16x16x32_bf16 v[12:15], v[218:221], v[32:35], v[12:15]
	ds_read_b128 v[50:53], v40 offset:37760
	ds_read_b128 v[214:217], v90 offset:32768
	ds_read_b128 v[218:221], v90 offset:32832
	s_waitcnt lgkmcnt(3)
	v_pk_mul_f32 v[10:11], v[10:11], v[224:225]
	v_pk_mul_f32 v[8:9], v[8:9], v[222:223]
	s_nop 1
	v_mfma_f32_16x16x32_bf16 v[8:11], v[226:229], v[36:39], v[8:11]
	v_mfma_f32_16x16x32_bf16 v[8:11], v[230:233], v[32:35], v[8:11]
	ds_read_b128 v[222:225], v40 offset:37824
	ds_read_b128 v[226:229], v90 offset:35072
	ds_read_b128 v[230:233], v90 offset:35136
	s_waitcnt lgkmcnt(3)
	v_pk_mul_f32 v[6:7], v[6:7], v[52:53]
	v_pk_mul_f32 v[4:5], v[4:5], v[50:51]
	s_nop 1
	v_mfma_f32_16x16x32_bf16 v[4:7], v[214:217], v[36:39], v[4:7]
	v_mfma_f32_16x16x32_bf16 v[4:7], v[218:221], v[32:35], v[4:7]
	s_waitcnt lgkmcnt(0)
	v_pk_mul_f32 v[2:3], v[2:3], v[224:225]
	v_pk_mul_f32 v[0:1], v[0:1], v[222:223]
	s_nop 1
	v_mfma_f32_16x16x32_bf16 v[0:3], v[226:229], v[36:39], v[0:3]
	v_mfma_f32_16x16x32_bf16 v[0:3], v[230:233], v[32:35], v[0:3]
	v_lshl_add_u64 v[32:33], v[44:45], 0, s[20:21]
	global_store_dwordx4 v[32:33], v[28:31], off
	global_store_dwordx4 v[32:33], v[24:27], off offset:64
	global_store_dwordx4 v[32:33], v[20:23], off offset:128
	global_store_dwordx4 v[32:33], v[16:19], off offset:192
	global_store_dwordx4 v[32:33], v[12:15], off offset:256
	global_store_dwordx4 v[32:33], v[8:11], off offset:320
	global_store_dwordx4 v[32:33], v[4:7], off offset:384
	global_store_dwordx4 v[32:33], v[0:3], off offset:448
	s_cbranch_vccz .LBB0_257
	v_mov_b32_e32 v69, v66
	v_pk_add_f32 v[0:1], v[48:49], v[68:69]
	s_lshl_b64 s[20:21], s[26:27], 9
	v_exp_f32_e32 v0, v0
	v_exp_f32_e32 v1, v1
	v_lshl_add_u64 v[2:3], v[46:47], 0, s[20:21]
	global_store_dwordx2 v[2:3], v[0:1], off
	s_branch .LBB0_257
